# attention softmax: row-max tree replaced by conservative per-lane row-sum trigger (exact max + rescale out of line), plain-add l-sum
# speedup vs baseline: 1.0463x; 1.0188x over previous
; DI unsigned pk2(float a, float b) { f32x2 v = {a, b}; return __builtin_bit_cast(unsigned, __builtin_convertvector(v, bfv2)); }
; DI float xor32_max(float x) { auto r = __builtin_amdgcn_permlane32_swap(__float_as_uint(x), __float_as_uint(x), false, false); return fmaxf(__uint_as_float(r[0]), __uint_as_float(r[1])); }
; DI float max3f(float a, float b, float c) { float r; asm("v_max3_f32 %0, %1, %2, %3" : "=v"(r) : "v"(a), "v"(b), "v"(c)); return r; }
; DI void attn_s(const unsigned char* sK, int tt, int qb, int qs, int sub, int l31, int h,
;                const bf16x8 (&qf)[4], f32x16 (&O)[4], float& m, float& l, bf16x8 (&pb)[4]) {
;     ...
;     float mx;
;     {
;         float t[11];
; #pragma unroll
;         for (int i = 0; i < 5; ++i) t[i] = max3f(st[0][3 * i], st[0][3 * i + 1], st[0][3 * i + 2]);
; #pragma unroll
;         for (int i = 0; i < 5; ++i) t[5 + i] = max3f(st[1][3 * i], st[1][3 * i + 1], st[1][3 * i + 2]);
;         t[10] = fmaxf(st[0][15], st[1][15]);
;         const float u0 = max3f(t[0], t[1], t[2]), u1 = max3f(t[3], t[4], t[5]), u2 = max3f(t[6], t[7], t[8]);
;         mx = max3f(max3f(u0, u1, u2), t[9], t[10]);
;     }
;     mx = xor32_max(mx);
;     if (tt == 0 || __builtin_amdgcn_ballot_w64(mx > 8.0f) != 0ull) {
;         const float delta = tt == 0 ? mx : fmaxf(mx, 0.f);
;         const float alpha = __builtin_amdgcn_exp2f(-delta);
;         m += delta;
;         l *= alpha;
; #pragma unroll
;         for (int d = 0; d < 4; ++d) O[d] = O[d] * alpha;
; #pragma unroll
;         for (int k2 = 0; k2 < 2; ++k2) st[k2] = st[k2] - delta;
;     }
; #pragma unroll
;     for (int k2 = 0; k2 < 2; ++k2)
; #pragma unroll
;         for (int i = 0; i < 16; ++i) st[k2][i] = __builtin_amdgcn_exp2f(st[k2][i]);
;     {
;         const f32x16 sv = st[0] + st[1];
;         const float ps = (((sv[0] + sv[1]) + (sv[2] + sv[3])) + ((sv[4] + sv[5]) + (sv[6] + sv[7]))) + (((sv[8] + sv[9]) + (sv[10] + sv[11])) + ((sv[12] + sv[13]) + (sv[14] + sv[15])));
;         l += ps;
;     }
; #pragma unroll
;     for (int k4 = 0; k4 < 4; ++k4) {
;         const int k2 = k4 >> 1, o8 = 8 * (k4 & 1);
;         u32x4 pk;
;         pk.x = pk2(st[k2][o8 + 0], st[k2][o8 + 1]); pk.y = pk2(st[k2][o8 + 2], st[k2][o8 + 3]);
;         pk.z = pk2(st[k2][o8 + 4], st[k2][o8 + 5]); pk.w = pk2(st[k2][o8 + 6], st[k2][o8 + 7]);
;         pb[k4] = __builtin_bit_cast(bf16x8, pk);
;     }
.Lpipe_nomask_l:
	v_exp_f32_e32 v82, v82
	v_exp_f32_e32 v83, v83
	v_exp_f32_e32 v84, v84
	v_exp_f32_e32 v85, v85
	v_exp_f32_e32 v86, v86
	v_exp_f32_e32 v87, v87
	v_exp_f32_e32 v88, v88
	v_exp_f32_e32 v89, v89
	v_exp_f32_e32 v90, v90
	v_exp_f32_e32 v91, v91
	v_exp_f32_e32 v92, v92
	v_exp_f32_e32 v93, v93
	v_exp_f32_e32 v94, v94
	v_exp_f32_e32 v95, v95
	v_exp_f32_e32 v96, v96
	v_exp_f32_e32 v97, v97
	v_exp_f32_e32 v66, v66
	v_exp_f32_e32 v67, v67
	v_exp_f32_e32 v68, v68
	v_exp_f32_e32 v69, v69
	v_exp_f32_e32 v70, v70
	v_exp_f32_e32 v71, v71
	v_exp_f32_e32 v72, v72
	v_exp_f32_e32 v73, v73
	v_exp_f32_e32 v74, v74
	v_exp_f32_e32 v75, v75
	v_exp_f32_e32 v76, v76
	v_exp_f32_e32 v77, v77
	v_exp_f32_e32 v78, v78
	v_exp_f32_e32 v79, v79
	v_exp_f32_e32 v80, v80
	v_exp_f32_e32 v81, v81
	v_cvt_pk_bf16_f32 v216, v82, v83
	v_cvt_pk_bf16_f32 v217, v84, v85
	v_cvt_pk_bf16_f32 v218, v86, v87
	v_cvt_pk_bf16_f32 v219, v88, v89
	v_cvt_pk_bf16_f32 v220, v90, v91
	v_cvt_pk_bf16_f32 v221, v92, v93
	v_cvt_pk_bf16_f32 v222, v94, v95
	v_cvt_pk_bf16_f32 v223, v96, v97
	v_cvt_pk_bf16_f32 v224, v66, v67
	v_cvt_pk_bf16_f32 v225, v68, v69
	v_cvt_pk_bf16_f32 v226, v70, v71
	v_cvt_pk_bf16_f32 v227, v72, v73
	v_cvt_pk_bf16_f32 v228, v74, v75
	v_cvt_pk_bf16_f32 v229, v76, v77
	v_cvt_pk_bf16_f32 v230, v78, v79
	v_cvt_pk_bf16_f32 v231, v80, v81
	v_add_f32_e32 v160, v82, v66
	v_add_f32_e32 v161, v83, v67
	v_add_f32_e32 v162, v84, v68
	v_add_f32_e32 v163, v85, v69
	v_add_f32_e32 v164, v86, v70
	v_add_f32_e32 v165, v87, v71
	v_add_f32_e32 v166, v88, v72
	v_add_f32_e32 v167, v89, v73
	v_add_f32_e32 v168, v90, v74
	v_add_f32_e32 v169, v91, v75
	v_add_f32_e32 v170, v92, v76
	v_add_f32_e32 v171, v93, v77
	v_add_f32_e32 v196, v94, v78
	v_add_f32_e32 v197, v95, v79
	v_add_f32_e32 v198, v96, v80
	v_add_f32_e32 v199, v97, v81
	s_mov_b32 s14, 0x43800000
	v_add_f32_e32 v160, v160, v168
	v_add_f32_e32 v161, v161, v169
	v_add_f32_e32 v162, v162, v170
	v_add_f32_e32 v163, v163, v171
	v_add_f32_e32 v164, v164, v196
	v_add_f32_e32 v165, v165, v197
	v_add_f32_e32 v166, v166, v198
	v_add_f32_e32 v167, v167, v199
	v_add_f32_e32 v160, v160, v164
	v_add_f32_e32 v161, v161, v165
	v_add_f32_e32 v162, v162, v166
	v_add_f32_e32 v163, v163, v167
	v_add_f32_e32 v160, v160, v162
	v_add_f32_e32 v161, v161, v163
	v_add_f32_e32 v159, v160, v161
	v_add_u32_e32 v158, 64, v158
	v_cmp_lt_f32_e32 vcc, s14, v159
	s_cbranch_vccnz .Lpipe_rare
.Lpipe_rejoin:
	v_add_f32_e32 v1, v1, v159
	v_lshl_add_u64 v[144:145], v[144:145], 0, s[90:91]
	v_lshl_add_u64 v[142:143], v[142:143], 0, s[88:89]
	v_lshl_add_u64 v[184:185], v[144:145], 0, s[92:93]
	v_add_co_u32_e32 v238, vcc, 0x80000, v142
	s_mul_i32 s98, s7, 0x8c00
	s_nop 0
	v_addc_co_u32_e32 v239, vcc, 0, v143, vcc
	v_add3_u32 v237, s98, v155, v154
	s_add_i32 s4, s7, 1
	s_cmp_lg_u32 s7, 2
	s_cselect_b32 s4, s4, 0
	s_mul_i32 s4, s4, 0x8c00
	v_add3_u32 v232, s4, v140, v139
	v_add3_u32 v233, s4, v140, v141
	v_add3_u32 v234, s4, v150, v151
	v_add_u32_e32 v235, v234, v153
	v_add_u32_e32 v234, v234, v152
	v_add_u32_e32 v235, 0x4000, v235
	v_add_u32_e32 v234, 0x4000, v234
	s_mov_b32 s13, s7
	s_add_i32 s4, s7, 1
	s_cmp_lg_u32 s7, 2
	s_cselect_b32 s7, s4, 0
	s_add_i32 s12, s12, 1
	s_cmp_eq_u32 s11, s12
	s_cbranch_scc1 .Lpipe_final
	s_barrier
	s_setprio 1
	ds_read_b128 v[160:163], v237
	ds_read_b128 v[164:167], v237 offset:32
	ds_read_b128 v[168:171], v237 offset:8704
	ds_read_b128 v[196:199], v237 offset:8736
	s_waitcnt lgkmcnt(8)
	v_mfma_f32_32x32x16_bf16 v[50:65], v[172:175], v[216:219], v[50:65]
	ds_read_b128 v[172:175], v237 offset:64
	v_mfma_f32_32x32x16_bf16 v[34:49], v[176:179], v[216:219], v[34:49]
	ds_read_b128 v[176:179], v237 offset:96
	v_mfma_f32_32x32x16_bf16 v[18:33], v[180:183], v[216:219], v[18:33]
	ds_read_b128 v[180:183], v237 offset:8768
	v_mfma_f32_32x32x16_bf16 v[2:17], v[192:195], v[216:219], v[2:17]
	ds_read_b128 v[192:195], v237 offset:8800
	s_waitcnt lgkmcnt(8)
	v_mfma_f32_32x32x16_bf16 v[50:65], v[200:203], v[220:223], v[50:65]
	ds_read_b128 v[200:203], v191 offset:17472
	v_mfma_f32_32x32x16_bf16 v[34:49], v[204:207], v[220:223], v[34:49]
	ds_read_b128 v[204:207], v191 offset:22080
	v_mfma_f32_32x32x16_bf16 v[18:33], v[208:211], v[220:223], v[18:33]
	ds_read_b128 v[208:211], v191 offset:26688
	v_mfma_f32_32x32x16_bf16 v[2:17], v[212:215], v[220:223], v[2:17]
	ds_read_b128 v[212:215], v191 offset:31296
	s_waitcnt lgkmcnt(8)
	v_mfma_f32_32x32x16_bf16 v[82:97], v[160:163], v[100:103], v[240:255]
	ds_read_b128 v[160:163], v191 offset:17504
	v_mfma_f32_32x32x16_bf16 v[66:81], v[168:171], v[100:103], v[240:255]
	ds_read_b128 v[168:171], v191 offset:26720
	v_mfma_f32_32x32x16_bf16 v[82:97], v[164:167], v[104:107], v[82:97]
	ds_read_b128 v[164:167], v191 offset:22112
	v_mfma_f32_32x32x16_bf16 v[66:81], v[196:199], v[104:107], v[66:81]
	ds_read_b128 v[196:199], v191 offset:31328
	s_waitcnt lgkmcnt(8)
	v_mfma_f32_32x32x16_bf16 v[82:97], v[172:175], v[108:111], v[82:97]
	s_waitcnt vmcnt(3)
	ds_write_b128 v232, v[116:119]
	v_mfma_f32_32x32x16_bf16 v[66:81], v[180:183], v[108:111], v[66:81]
	s_waitcnt vmcnt(2)
	ds_write_b128 v233, v[120:123]
	v_mfma_f32_32x32x16_bf16 v[82:97], v[176:179], v[112:115], v[82:97]
	s_waitcnt vmcnt(1)
	ds_write2_b64 v234, v[124:125], v[126:127] offset0:128 offset1:130
	v_mfma_f32_32x32x16_bf16 v[66:81], v[192:195], v[112:115], v[66:81]
	s_waitcnt vmcnt(0)
	ds_write2_b64 v235, v[128:129], v[130:131] offset0:128 offset1:130
	s_add_i32 s14, s12, 0x43
	s_cmp_ge_i32 s14, s6
	s_cbranch_scc1 .Lpipe_k2_nopf
	s_waitcnt lgkmcnt(8)
	v_mfma_f32_32x32x16_bf16 v[50:65], v[200:203], v[224:227], v[50:65]
	global_load_dwordx4 v[116:119], v[144:145], off
	v_mfma_f32_32x32x16_bf16 v[34:49], v[204:207], v[224:227], v[34:49]
	global_load_dwordx4 v[120:123], v[184:185], off
	v_mfma_f32_32x32x16_bf16 v[18:33], v[208:211], v[224:227], v[18:33]
	global_load_dwordx4 v[124:127], v[142:143], off
	v_mfma_f32_32x32x16_bf16 v[2:17], v[212:215], v[224:227], v[2:17]
	global_load_dwordx4 v[128:131], v[238:239], off
	s_branch .Lpipe_k3

; DI float xor32_max(float x) { auto r = __builtin_amdgcn_permlane32_swap(__float_as_uint(x), __float_as_uint(x), false, false); return fmaxf(__uint_as_float(r[0]), __uint_as_float(r[1])); }
; DI void attn_s(const unsigned char* sK, int tt, int qb, int qs, int sub, int l31, int h,
;                const bf16x8 (&qf)[4], f32x16 (&O)[4], float& m, float& l, bf16x8 (&pb)[4]) {
;     ...
;     mx = xor32_max(mx);
;     if (tt == 0 || __builtin_amdgcn_ballot_w64(mx > 8.0f) != 0ull) {
;         const float delta = tt == 0 ? mx : fmaxf(mx, 0.f);
;         const float alpha = __builtin_amdgcn_exp2f(-delta);
;         m += delta;
;         l *= alpha;
; #pragma unroll
;         for (int d = 0; d < 4; ++d) O[d] = O[d] * alpha;
; #pragma unroll
;         for (int k2 = 0; k2 < 2; ++k2) st[k2] = st[k2] - delta;
;     }
.Lpipe_rare:
	v_max3_f32 v160, v82, v83, v84
	v_max3_f32 v161, v85, v86, v87
	v_max3_f32 v162, v88, v89, v90
	v_max3_f32 v163, v91, v92, v93
	v_max3_f32 v164, v94, v95, v96
	v_max3_f32 v165, v66, v67, v68
	v_max3_f32 v166, v69, v70, v71
	v_max3_f32 v167, v72, v73, v74
	v_max3_f32 v168, v75, v76, v77
	v_max3_f32 v169, v78, v79, v80
	v_max_f32_e32 v170, v81, v97
	v_max3_f32 v160, v160, v161, v162
	v_max3_f32 v163, v163, v164, v165
	v_max3_f32 v166, v166, v167, v168
	v_max_f32_e32 v169, v169, v170
	v_max3_f32 v160, v160, v163, v166
	v_max_f32_e32 v160, v160, v169
	v_mov_b32_e32 v161, v160
	s_nop 1
	v_permlane32_swap_b32_e32 v160, v161
	s_nop 1
	v_max_f32_e32 v160, v160, v161
	s_nop 1
	v_cmp_lt_f32_e32 vcc, s14, v160
	s_cbranch_vccz .Lpipe_rejoin
	v_max_f32_e32 v160, 1.0, v160
	v_log_f32_e32 v161, v160
	s_nop 1
	v_exp_f32_e64 v160, -v161
	v_add_f32_e32 v157, v157, v161
	v_xor_b32_e32 v240, 0x80000000, v157
	v_mov_b32_e32 v241, v240
	v_mov_b32_e32 v242, v240
	v_mov_b32_e32 v243, v240
	v_mov_b32_e32 v244, v240
	v_mov_b32_e32 v245, v240
	v_mov_b32_e32 v246, v240
	v_mov_b32_e32 v247, v240
	v_mov_b32_e32 v248, v240
	v_mov_b32_e32 v249, v240
	v_mov_b32_e32 v250, v240
	v_mov_b32_e32 v251, v240
	v_mov_b32_e32 v252, v240
	v_mov_b32_e32 v253, v240
	v_mov_b32_e32 v254, v240
	v_mov_b32_e32 v255, v240
	v_mul_f32_e32 v1, v1, v160
	v_mul_f32_e32 v159, v159, v160
	v_pk_mul_f32 v[64:65], v[64:65], v[160:161] op_sel_hi:[1,0]
	v_pk_mul_f32 v[62:63], v[62:63], v[160:161] op_sel_hi:[1,0]
	v_pk_mul_f32 v[60:61], v[60:61], v[160:161] op_sel_hi:[1,0]
	v_pk_mul_f32 v[58:59], v[58:59], v[160:161] op_sel_hi:[1,0]
	v_pk_mul_f32 v[56:57], v[56:57], v[160:161] op_sel_hi:[1,0]
	v_pk_mul_f32 v[54:55], v[54:55], v[160:161] op_sel_hi:[1,0]
	v_pk_mul_f32 v[52:53], v[52:53], v[160:161] op_sel_hi:[1,0]
	v_pk_mul_f32 v[50:51], v[50:51], v[160:161] op_sel_hi:[1,0]
	v_pk_mul_f32 v[48:49], v[48:49], v[160:161] op_sel_hi:[1,0]
	v_pk_mul_f32 v[46:47], v[46:47], v[160:161] op_sel_hi:[1,0]
	v_pk_mul_f32 v[44:45], v[44:45], v[160:161] op_sel_hi:[1,0]
	v_pk_mul_f32 v[42:43], v[42:43], v[160:161] op_sel_hi:[1,0]
	v_pk_mul_f32 v[40:41], v[40:41], v[160:161] op_sel_hi:[1,0]
	v_pk_mul_f32 v[38:39], v[38:39], v[160:161] op_sel_hi:[1,0]
	v_pk_mul_f32 v[36:37], v[36:37], v[160:161] op_sel_hi:[1,0]
	v_pk_mul_f32 v[34:35], v[34:35], v[160:161] op_sel_hi:[1,0]
	v_pk_mul_f32 v[32:33], v[32:33], v[160:161] op_sel_hi:[1,0]
	v_pk_mul_f32 v[30:31], v[30:31], v[160:161] op_sel_hi:[1,0]
	v_pk_mul_f32 v[28:29], v[28:29], v[160:161] op_sel_hi:[1,0]
	v_pk_mul_f32 v[26:27], v[26:27], v[160:161] op_sel_hi:[1,0]
	v_pk_mul_f32 v[24:25], v[24:25], v[160:161] op_sel_hi:[1,0]
	v_pk_mul_f32 v[22:23], v[22:23], v[160:161] op_sel_hi:[1,0]
	v_pk_mul_f32 v[20:21], v[20:21], v[160:161] op_sel_hi:[1,0]
	v_pk_mul_f32 v[18:19], v[18:19], v[160:161] op_sel_hi:[1,0]
	v_pk_mul_f32 v[16:17], v[16:17], v[160:161] op_sel_hi:[1,0]
	v_pk_mul_f32 v[14:15], v[14:15], v[160:161] op_sel_hi:[1,0]
	v_pk_mul_f32 v[12:13], v[12:13], v[160:161] op_sel_hi:[1,0]
	v_pk_mul_f32 v[10:11], v[10:11], v[160:161] op_sel_hi:[1,0]
	v_pk_mul_f32 v[8:9], v[8:9], v[160:161] op_sel_hi:[1,0]
	v_pk_mul_f32 v[6:7], v[6:7], v[160:161] op_sel_hi:[1,0]
	v_pk_mul_f32 v[4:5], v[4:5], v[160:161] op_sel_hi:[1,0]
	v_pk_mul_f32 v[2:3], v[2:3], v[160:161] op_sel_hi:[1,0]
	v_mul_f32_e32 v66, v66, v160
	v_mul_f32_e32 v67, v67, v160
	v_mul_f32_e32 v68, v68, v160
	v_mul_f32_e32 v69, v69, v160
	v_mul_f32_e32 v70, v70, v160
	v_mul_f32_e32 v71, v71, v160
	v_mul_f32_e32 v72, v72, v160
	v_mul_f32_e32 v73, v73, v160
	v_mul_f32_e32 v74, v74, v160
	v_mul_f32_e32 v75, v75, v160
	v_mul_f32_e32 v76, v76, v160
	v_mul_f32_e32 v77, v77, v160
	v_mul_f32_e32 v78, v78, v160
	v_mul_f32_e32 v79, v79, v160
	v_mul_f32_e32 v80, v80, v160
	v_mul_f32_e32 v81, v81, v160
	v_mul_f32_e32 v82, v82, v160
	v_mul_f32_e32 v83, v83, v160
	v_mul_f32_e32 v84, v84, v160
	v_mul_f32_e32 v85, v85, v160
	v_mul_f32_e32 v86, v86, v160
	v_mul_f32_e32 v87, v87, v160
	v_mul_f32_e32 v88, v88, v160
	v_mul_f32_e32 v89, v89, v160
	v_mul_f32_e32 v90, v90, v160
	v_mul_f32_e32 v91, v91, v160
	v_mul_f32_e32 v92, v92, v160
	v_mul_f32_e32 v93, v93, v160
	v_mul_f32_e32 v94, v94, v160
	v_mul_f32_e32 v95, v95, v160
	v_mul_f32_e32 v96, v96, v160
	v_mul_f32_e32 v97, v97, v160
	v_cvt_pk_bf16_f32 v216, v82, v83
	v_cvt_pk_bf16_f32 v217, v84, v85
	v_cvt_pk_bf16_f32 v218, v86, v87
	v_cvt_pk_bf16_f32 v219, v88, v89
	v_cvt_pk_bf16_f32 v220, v90, v91
	v_cvt_pk_bf16_f32 v221, v92, v93
	v_cvt_pk_bf16_f32 v222, v94, v95
	v_cvt_pk_bf16_f32 v223, v96, v97
	v_cvt_pk_bf16_f32 v224, v66, v67
	v_cvt_pk_bf16_f32 v225, v68, v69
	v_cvt_pk_bf16_f32 v226, v70, v71
	v_cvt_pk_bf16_f32 v227, v72, v73
	v_cvt_pk_bf16_f32 v228, v74, v75
	v_cvt_pk_bf16_f32 v229, v76, v77
	v_cvt_pk_bf16_f32 v230, v78, v79
	v_cvt_pk_bf16_f32 v231, v80, v81
	s_branch .Lpipe_rejoin
